# sample attention score loop: 4-deep K load pipeline (tail path), on top of transpose MLP
# speedup vs baseline: 1.0049x; 1.0049x over previous
.LBB0_849:
	s_ashr_i32 s59, s58, 31
	s_lshl_b64 s[40:41], s[58:59], 19
	s_or_b64 s[40:41], s[40:41], s[48:49]
	s_lshl_b64 s[62:63], s[40:41], 2
	s_waitcnt lgkmcnt(0)
	s_add_u32 s40, s64, s62
	s_addc_u32 s41, s65, s63
	s_add_i32 s58, s67, 0x2000
	s_ashr_i32 s59, s58, 31
	v_lshl_add_u64 v[0:1], s[40:41], 0, v[66:67]
	s_and_b32 s40, s66, 3
	s_lshl_b64 s[64:65], s[58:59], 12
	s_lshl_b32 s40, s40, 10
	s_or_b32 s64, s64, s40
	v_mov_b32_e32 v4, 0
	v_lshl_add_u64 v[28:29], v[0:1], 0, v[64:65]
	v_lshl_add_u64 v[30:31], v[70:71], 0, s[64:65]
	s_mov_b64 s[64:65], 0
	v_mov_b32_e32 v34, v90
	v_mov_b32_e32 v5, v4
	v_mov_b32_e32 v6, v4
	v_mov_b32_e32 v7, v4
	v_mov_b32_e32 v0, v4
	v_mov_b32_e32 v1, v4
	v_mov_b32_e32 v2, v4
	v_mov_b32_e32 v3, v4
	s_and_b64 vcc, exec, s[14:15]
	s_cbranch_vccnz .LBB0_851
	s_mov_b64 s[40:41], 0x20000
	v_lshl_add_u64 v[222:223], v[28:29], 0, s[40:41]
	global_load_dwordx4 v[122:125], v[28:29], off
	global_load_dwordx4 v[126:129], v[28:29], off offset:16
	global_load_dwordx4 v[130:133], v[222:223], off
	global_load_dwordx4 v[134:137], v[222:223], off offset:16
	global_load_dwordx4 v[138:141], v[28:29], off offset:128
	global_load_dwordx4 v[142:145], v[28:29], off offset:144
	global_load_dwordx4 v[146:149], v[222:223], off offset:128
	global_load_dwordx4 v[150:153], v[222:223], off offset:144
	global_load_dwordx4 v[166:169], v[28:29], off offset:256
	global_load_dwordx4 v[170:173], v[28:29], off offset:272
	global_load_dwordx4 v[174:177], v[222:223], off offset:256
	global_load_dwordx4 v[178:181], v[222:223], off offset:272
	global_load_dwordx4 v[198:201], v[28:29], off offset:384
	global_load_dwordx4 v[202:205], v[28:29], off offset:400
	global_load_dwordx4 v[206:209], v[222:223], off offset:384
	global_load_dwordx4 v[210:213], v[222:223], off offset:400
	ds_read_b128 v[214:217], v34
	ds_read_b128 v[218:221], v34 offset:64
	s_waitcnt vmcnt(12)
	s_waitcnt lgkmcnt(1)
	v_cndmask_b32_e64 v214, v214, 0, s[8:9]
	v_cndmask_b32_e64 v215, v215, 0, s[8:9]
	v_cndmask_b32_e64 v216, v216, 0, s[8:9]
	v_cndmask_b32_e64 v217, v217, 0, s[8:9]
	v_cvt_pk_bf16_f32 v122, v122, v123
	v_cvt_pk_bf16_f32 v123, v124, v125
	v_cvt_pk_bf16_f32 v124, v126, v127
	v_cvt_pk_bf16_f32 v125, v128, v129
	v_cvt_pk_bf16_f32 v130, v130, v131
	v_cvt_pk_bf16_f32 v131, v132, v133
	v_cvt_pk_bf16_f32 v132, v134, v135
	v_cvt_pk_bf16_f32 v133, v136, v137
	v_mfma_f32_16x16x32_bf16 v[4:7], v[122:125], v[214:217], v[4:7]
	s_nop 0
	v_mfma_f32_16x16x32_bf16 v[0:3], v[130:133], v[214:217], v[0:3]
	global_load_dwordx4 v[122:125], v[28:29], off offset:512
	global_load_dwordx4 v[126:129], v[28:29], off offset:528
	global_load_dwordx4 v[130:133], v[222:223], off offset:512
	global_load_dwordx4 v[134:137], v[222:223], off offset:528
	ds_read_b128 v[214:217], v34 offset:128
	s_waitcnt vmcnt(12)
	s_waitcnt lgkmcnt(1)
	v_cndmask_b32_e64 v218, v218, 0, s[8:9]
	v_cndmask_b32_e64 v219, v219, 0, s[8:9]
	v_cndmask_b32_e64 v220, v220, 0, s[8:9]
	v_cndmask_b32_e64 v221, v221, 0, s[8:9]
	v_cvt_pk_bf16_f32 v138, v138, v139
	v_cvt_pk_bf16_f32 v139, v140, v141
	v_cvt_pk_bf16_f32 v140, v142, v143
	v_cvt_pk_bf16_f32 v141, v144, v145
	v_cvt_pk_bf16_f32 v146, v146, v147
	v_cvt_pk_bf16_f32 v147, v148, v149
	v_cvt_pk_bf16_f32 v148, v150, v151
	v_cvt_pk_bf16_f32 v149, v152, v153
	v_mfma_f32_16x16x32_bf16 v[4:7], v[138:141], v[218:221], v[4:7]
	s_nop 0
	v_mfma_f32_16x16x32_bf16 v[0:3], v[146:149], v[218:221], v[0:3]
	global_load_dwordx4 v[138:141], v[28:29], off offset:640
	global_load_dwordx4 v[142:145], v[28:29], off offset:656
	global_load_dwordx4 v[146:149], v[222:223], off offset:640
	global_load_dwordx4 v[150:153], v[222:223], off offset:656
	ds_read_b128 v[218:221], v34 offset:192
	s_waitcnt vmcnt(12)
	s_waitcnt lgkmcnt(1)
	v_cndmask_b32_e64 v214, v214, 0, s[8:9]
	v_cndmask_b32_e64 v215, v215, 0, s[8:9]
	v_cndmask_b32_e64 v216, v216, 0, s[8:9]
	v_cndmask_b32_e64 v217, v217, 0, s[8:9]
	v_cvt_pk_bf16_f32 v166, v166, v167
	v_cvt_pk_bf16_f32 v167, v168, v169
	v_cvt_pk_bf16_f32 v168, v170, v171
	v_cvt_pk_bf16_f32 v169, v172, v173
	v_cvt_pk_bf16_f32 v174, v174, v175
	v_cvt_pk_bf16_f32 v175, v176, v177
	v_cvt_pk_bf16_f32 v176, v178, v179
	v_cvt_pk_bf16_f32 v177, v180, v181
	v_mfma_f32_16x16x32_bf16 v[4:7], v[166:169], v[214:217], v[4:7]
	s_nop 0
	v_mfma_f32_16x16x32_bf16 v[0:3], v[174:177], v[214:217], v[0:3]
	global_load_dwordx4 v[166:169], v[28:29], off offset:768
	global_load_dwordx4 v[170:173], v[28:29], off offset:784
	global_load_dwordx4 v[174:177], v[222:223], off offset:768
	global_load_dwordx4 v[178:181], v[222:223], off offset:784
	ds_read_b128 v[214:217], v34 offset:256
	s_waitcnt vmcnt(12)
	s_waitcnt lgkmcnt(1)
	v_cndmask_b32_e64 v218, v218, 0, s[8:9]
	v_cndmask_b32_e64 v219, v219, 0, s[8:9]
	v_cndmask_b32_e64 v220, v220, 0, s[8:9]
	v_cndmask_b32_e64 v221, v221, 0, s[8:9]
	v_cvt_pk_bf16_f32 v198, v198, v199
	v_cvt_pk_bf16_f32 v199, v200, v201
	v_cvt_pk_bf16_f32 v200, v202, v203
	v_cvt_pk_bf16_f32 v201, v204, v205
	v_cvt_pk_bf16_f32 v206, v206, v207
	v_cvt_pk_bf16_f32 v207, v208, v209
	v_cvt_pk_bf16_f32 v208, v210, v211
	v_cvt_pk_bf16_f32 v209, v212, v213
	v_mfma_f32_16x16x32_bf16 v[4:7], v[198:201], v[218:221], v[4:7]
	s_nop 0
	v_mfma_f32_16x16x32_bf16 v[0:3], v[206:209], v[218:221], v[0:3]
	global_load_dwordx4 v[198:201], v[28:29], off offset:896
	global_load_dwordx4 v[202:205], v[28:29], off offset:912
	global_load_dwordx4 v[206:209], v[222:223], off offset:896
	global_load_dwordx4 v[210:213], v[222:223], off offset:912
	ds_read_b128 v[218:221], v34 offset:320
	s_waitcnt vmcnt(12)
	s_waitcnt lgkmcnt(1)
	v_cndmask_b32_e64 v214, v214, 0, s[8:9]
	v_cndmask_b32_e64 v215, v215, 0, s[8:9]
	v_cndmask_b32_e64 v216, v216, 0, s[8:9]
	v_cndmask_b32_e64 v217, v217, 0, s[8:9]
	v_cvt_pk_bf16_f32 v122, v122, v123
	v_cvt_pk_bf16_f32 v123, v124, v125
	v_cvt_pk_bf16_f32 v124, v126, v127
	v_cvt_pk_bf16_f32 v125, v128, v129
	v_cvt_pk_bf16_f32 v130, v130, v131
	v_cvt_pk_bf16_f32 v131, v132, v133
	v_cvt_pk_bf16_f32 v132, v134, v135
	v_cvt_pk_bf16_f32 v133, v136, v137
	v_mfma_f32_16x16x32_bf16 v[4:7], v[122:125], v[214:217], v[4:7]
	s_nop 0
	v_mfma_f32_16x16x32_bf16 v[0:3], v[130:133], v[214:217], v[0:3]
	global_load_dwordx4 v[122:125], v[28:29], off offset:1024
	global_load_dwordx4 v[126:129], v[28:29], off offset:1040
	global_load_dwordx4 v[130:133], v[222:223], off offset:1024
	global_load_dwordx4 v[134:137], v[222:223], off offset:1040
	ds_read_b128 v[214:217], v34 offset:384
	s_waitcnt vmcnt(12)
	s_waitcnt lgkmcnt(1)
	v_cndmask_b32_e64 v218, v218, 0, s[8:9]
	v_cndmask_b32_e64 v219, v219, 0, s[8:9]
	v_cndmask_b32_e64 v220, v220, 0, s[8:9]
	v_cndmask_b32_e64 v221, v221, 0, s[8:9]
	v_cvt_pk_bf16_f32 v138, v138, v139
	v_cvt_pk_bf16_f32 v139, v140, v141
	v_cvt_pk_bf16_f32 v140, v142, v143
	v_cvt_pk_bf16_f32 v141, v144, v145
	v_cvt_pk_bf16_f32 v146, v146, v147
	v_cvt_pk_bf16_f32 v147, v148, v149
	v_cvt_pk_bf16_f32 v148, v150, v151
	v_cvt_pk_bf16_f32 v149, v152, v153
	v_mfma_f32_16x16x32_bf16 v[4:7], v[138:141], v[218:221], v[4:7]
	s_nop 0
	v_mfma_f32_16x16x32_bf16 v[0:3], v[146:149], v[218:221], v[0:3]
	global_load_dwordx4 v[138:141], v[28:29], off offset:1152
	global_load_dwordx4 v[142:145], v[28:29], off offset:1168
	global_load_dwordx4 v[146:149], v[222:223], off offset:1152
	global_load_dwordx4 v[150:153], v[222:223], off offset:1168
	ds_read_b128 v[218:221], v34 offset:448
	s_waitcnt vmcnt(12)
	s_waitcnt lgkmcnt(1)
	v_cndmask_b32_e64 v214, v214, 0, s[8:9]
	v_cndmask_b32_e64 v215, v215, 0, s[8:9]
	v_cndmask_b32_e64 v216, v216, 0, s[8:9]
	v_cndmask_b32_e64 v217, v217, 0, s[8:9]
	v_cvt_pk_bf16_f32 v166, v166, v167
	v_cvt_pk_bf16_f32 v167, v168, v169
	v_cvt_pk_bf16_f32 v168, v170, v171
	v_cvt_pk_bf16_f32 v169, v172, v173
	v_cvt_pk_bf16_f32 v174, v174, v175
	v_cvt_pk_bf16_f32 v175, v176, v177
	v_cvt_pk_bf16_f32 v176, v178, v179
	v_cvt_pk_bf16_f32 v177, v180, v181
	v_mfma_f32_16x16x32_bf16 v[4:7], v[166:169], v[214:217], v[4:7]
	s_nop 0
	v_mfma_f32_16x16x32_bf16 v[0:3], v[174:177], v[214:217], v[0:3]
	global_load_dwordx4 v[166:169], v[28:29], off offset:1280
	global_load_dwordx4 v[170:173], v[28:29], off offset:1296
	global_load_dwordx4 v[174:177], v[222:223], off offset:1280
	global_load_dwordx4 v[178:181], v[222:223], off offset:1296
	ds_read_b128 v[214:217], v34 offset:512
	s_waitcnt vmcnt(12)
	s_waitcnt lgkmcnt(1)
	v_cndmask_b32_e64 v218, v218, 0, s[8:9]
	v_cndmask_b32_e64 v219, v219, 0, s[8:9]
	v_cndmask_b32_e64 v220, v220, 0, s[8:9]
	v_cndmask_b32_e64 v221, v221, 0, s[8:9]
	v_cvt_pk_bf16_f32 v198, v198, v199
	v_cvt_pk_bf16_f32 v199, v200, v201
	v_cvt_pk_bf16_f32 v200, v202, v203
	v_cvt_pk_bf16_f32 v201, v204, v205
	v_cvt_pk_bf16_f32 v206, v206, v207
	v_cvt_pk_bf16_f32 v207, v208, v209
	v_cvt_pk_bf16_f32 v208, v210, v211
	v_cvt_pk_bf16_f32 v209, v212, v213
	v_mfma_f32_16x16x32_bf16 v[4:7], v[198:201], v[218:221], v[4:7]
	s_nop 0
	v_mfma_f32_16x16x32_bf16 v[0:3], v[206:209], v[218:221], v[0:3]
	global_load_dwordx4 v[198:201], v[28:29], off offset:1408
	global_load_dwordx4 v[202:205], v[28:29], off offset:1424
	global_load_dwordx4 v[206:209], v[222:223], off offset:1408
	global_load_dwordx4 v[210:213], v[222:223], off offset:1424
	ds_read_b128 v[218:221], v34 offset:576
	s_waitcnt vmcnt(12)
	s_waitcnt lgkmcnt(1)
	v_cndmask_b32_e64 v214, v214, 0, s[8:9]
	v_cndmask_b32_e64 v215, v215, 0, s[8:9]
	v_cndmask_b32_e64 v216, v216, 0, s[8:9]
	v_cndmask_b32_e64 v217, v217, 0, s[8:9]
	v_cvt_pk_bf16_f32 v122, v122, v123
	v_cvt_pk_bf16_f32 v123, v124, v125
	v_cvt_pk_bf16_f32 v124, v126, v127
	v_cvt_pk_bf16_f32 v125, v128, v129
	v_cvt_pk_bf16_f32 v130, v130, v131
	v_cvt_pk_bf16_f32 v131, v132, v133
	v_cvt_pk_bf16_f32 v132, v134, v135
	v_cvt_pk_bf16_f32 v133, v136, v137
	v_mfma_f32_16x16x32_bf16 v[4:7], v[122:125], v[214:217], v[4:7]
	s_nop 0
	v_mfma_f32_16x16x32_bf16 v[0:3], v[130:133], v[214:217], v[0:3]
	global_load_dwordx4 v[122:125], v[28:29], off offset:1536
	global_load_dwordx4 v[126:129], v[28:29], off offset:1552
	global_load_dwordx4 v[130:133], v[222:223], off offset:1536
	global_load_dwordx4 v[134:137], v[222:223], off offset:1552
	ds_read_b128 v[214:217], v34 offset:640
	s_waitcnt vmcnt(12)
	s_waitcnt lgkmcnt(1)
	v_cndmask_b32_e64 v218, v218, 0, s[8:9]
	v_cndmask_b32_e64 v219, v219, 0, s[8:9]
	v_cndmask_b32_e64 v220, v220, 0, s[8:9]
	v_cndmask_b32_e64 v221, v221, 0, s[8:9]
	v_cvt_pk_bf16_f32 v138, v138, v139
	v_cvt_pk_bf16_f32 v139, v140, v141
	v_cvt_pk_bf16_f32 v140, v142, v143
	v_cvt_pk_bf16_f32 v141, v144, v145
	v_cvt_pk_bf16_f32 v146, v146, v147
	v_cvt_pk_bf16_f32 v147, v148, v149
	v_cvt_pk_bf16_f32 v148, v150, v151
	v_cvt_pk_bf16_f32 v149, v152, v153
	v_mfma_f32_16x16x32_bf16 v[4:7], v[138:141], v[218:221], v[4:7]
	s_nop 0
	v_mfma_f32_16x16x32_bf16 v[0:3], v[146:149], v[218:221], v[0:3]
	global_load_dwordx4 v[138:141], v[28:29], off offset:1664
	global_load_dwordx4 v[142:145], v[28:29], off offset:1680
	global_load_dwordx4 v[146:149], v[222:223], off offset:1664
	global_load_dwordx4 v[150:153], v[222:223], off offset:1680
	ds_read_b128 v[218:221], v34 offset:704
	s_waitcnt vmcnt(12)
	s_waitcnt lgkmcnt(1)
	v_cndmask_b32_e64 v214, v214, 0, s[8:9]
	v_cndmask_b32_e64 v215, v215, 0, s[8:9]
	v_cndmask_b32_e64 v216, v216, 0, s[8:9]
	v_cndmask_b32_e64 v217, v217, 0, s[8:9]
	v_cvt_pk_bf16_f32 v166, v166, v167
	v_cvt_pk_bf16_f32 v167, v168, v169
	v_cvt_pk_bf16_f32 v168, v170, v171
	v_cvt_pk_bf16_f32 v169, v172, v173
	v_cvt_pk_bf16_f32 v174, v174, v175
	v_cvt_pk_bf16_f32 v175, v176, v177
	v_cvt_pk_bf16_f32 v176, v178, v179
	v_cvt_pk_bf16_f32 v177, v180, v181
	v_mfma_f32_16x16x32_bf16 v[4:7], v[166:169], v[214:217], v[4:7]
	s_nop 0
	v_mfma_f32_16x16x32_bf16 v[0:3], v[174:177], v[214:217], v[0:3]
	global_load_dwordx4 v[166:169], v[28:29], off offset:1792
	global_load_dwordx4 v[170:173], v[28:29], off offset:1808
	global_load_dwordx4 v[174:177], v[222:223], off offset:1792
	global_load_dwordx4 v[178:181], v[222:223], off offset:1808
	ds_read_b128 v[214:217], v34 offset:768
	s_waitcnt vmcnt(12)
	s_waitcnt lgkmcnt(1)
	v_cndmask_b32_e64 v218, v218, 0, s[8:9]
	v_cndmask_b32_e64 v219, v219, 0, s[8:9]
	v_cndmask_b32_e64 v220, v220, 0, s[8:9]
	v_cndmask_b32_e64 v221, v221, 0, s[8:9]
	v_cvt_pk_bf16_f32 v198, v198, v199
	v_cvt_pk_bf16_f32 v199, v200, v201
	v_cvt_pk_bf16_f32 v200, v202, v203
	v_cvt_pk_bf16_f32 v201, v204, v205
	v_cvt_pk_bf16_f32 v206, v206, v207
	v_cvt_pk_bf16_f32 v207, v208, v209
	v_cvt_pk_bf16_f32 v208, v210, v211
	v_cvt_pk_bf16_f32 v209, v212, v213
	v_mfma_f32_16x16x32_bf16 v[4:7], v[198:201], v[218:221], v[4:7]
	s_nop 0
	v_mfma_f32_16x16x32_bf16 v[0:3], v[206:209], v[218:221], v[0:3]
	global_load_dwordx4 v[198:201], v[28:29], off offset:1920
	global_load_dwordx4 v[202:205], v[28:29], off offset:1936
	global_load_dwordx4 v[206:209], v[222:223], off offset:1920
	global_load_dwordx4 v[210:213], v[222:223], off offset:1936
	ds_read_b128 v[218:221], v34 offset:832
	s_waitcnt vmcnt(12)
	s_waitcnt lgkmcnt(1)
	v_cndmask_b32_e64 v214, v214, 0, s[8:9]
	v_cndmask_b32_e64 v215, v215, 0, s[8:9]
	v_cndmask_b32_e64 v216, v216, 0, s[8:9]
	v_cndmask_b32_e64 v217, v217, 0, s[8:9]
	v_cvt_pk_bf16_f32 v122, v122, v123
	v_cvt_pk_bf16_f32 v123, v124, v125
	v_cvt_pk_bf16_f32 v124, v126, v127
	v_cvt_pk_bf16_f32 v125, v128, v129
	v_cvt_pk_bf16_f32 v130, v130, v131
	v_cvt_pk_bf16_f32 v131, v132, v133
	v_cvt_pk_bf16_f32 v132, v134, v135
	v_cvt_pk_bf16_f32 v133, v136, v137
	v_mfma_f32_16x16x32_bf16 v[4:7], v[122:125], v[214:217], v[4:7]
	s_nop 0
	v_mfma_f32_16x16x32_bf16 v[0:3], v[130:133], v[214:217], v[0:3]
	ds_read_b128 v[214:217], v34 offset:896
	s_waitcnt vmcnt(8)
	s_waitcnt lgkmcnt(1)
	v_cndmask_b32_e64 v218, v218, 0, s[8:9]
	v_cndmask_b32_e64 v219, v219, 0, s[8:9]
	v_cndmask_b32_e64 v220, v220, 0, s[8:9]
	v_cndmask_b32_e64 v221, v221, 0, s[8:9]
	v_cvt_pk_bf16_f32 v138, v138, v139
	v_cvt_pk_bf16_f32 v139, v140, v141
	v_cvt_pk_bf16_f32 v140, v142, v143
	v_cvt_pk_bf16_f32 v141, v144, v145
	v_cvt_pk_bf16_f32 v146, v146, v147
	v_cvt_pk_bf16_f32 v147, v148, v149
	v_cvt_pk_bf16_f32 v148, v150, v151
	v_cvt_pk_bf16_f32 v149, v152, v153
	v_mfma_f32_16x16x32_bf16 v[4:7], v[138:141], v[218:221], v[4:7]
	s_nop 0
	v_mfma_f32_16x16x32_bf16 v[0:3], v[146:149], v[218:221], v[0:3]
	ds_read_b128 v[218:221], v34 offset:960
	s_waitcnt vmcnt(4)
	s_waitcnt lgkmcnt(1)
	v_cndmask_b32_e64 v214, v214, 0, s[8:9]
	v_cndmask_b32_e64 v215, v215, 0, s[8:9]
	v_cndmask_b32_e64 v216, v216, 0, s[8:9]
	v_cndmask_b32_e64 v217, v217, 0, s[8:9]
	v_cvt_pk_bf16_f32 v166, v166, v167
	v_cvt_pk_bf16_f32 v167, v168, v169
	v_cvt_pk_bf16_f32 v168, v170, v171
	v_cvt_pk_bf16_f32 v169, v172, v173
	v_cvt_pk_bf16_f32 v174, v174, v175
	v_cvt_pk_bf16_f32 v175, v176, v177
	v_cvt_pk_bf16_f32 v176, v178, v179
	v_cvt_pk_bf16_f32 v177, v180, v181
	v_mfma_f32_16x16x32_bf16 v[4:7], v[166:169], v[214:217], v[4:7]
	s_nop 0
	v_mfma_f32_16x16x32_bf16 v[0:3], v[174:177], v[214:217], v[0:3]
	s_waitcnt vmcnt(0)
	s_waitcnt lgkmcnt(0)
	v_cndmask_b32_e64 v218, v218, 0, s[8:9]
	v_cndmask_b32_e64 v219, v219, 0, s[8:9]
	v_cndmask_b32_e64 v220, v220, 0, s[8:9]
	v_cndmask_b32_e64 v221, v221, 0, s[8:9]
	v_cvt_pk_bf16_f32 v198, v198, v199
	v_cvt_pk_bf16_f32 v199, v200, v201
	v_cvt_pk_bf16_f32 v200, v202, v203
	v_cvt_pk_bf16_f32 v201, v204, v205
	v_cvt_pk_bf16_f32 v206, v206, v207
	v_cvt_pk_bf16_f32 v207, v208, v209
	v_cvt_pk_bf16_f32 v208, v210, v211
	v_cvt_pk_bf16_f32 v209, v212, v213
	v_mfma_f32_16x16x32_bf16 v[4:7], v[198:201], v[218:221], v[4:7]
	s_nop 0
	v_mfma_f32_16x16x32_bf16 v[0:3], v[206:209], v[218:221], v[0:3]
	s_nop 7
	s_branch .LBB0_883
